# attn_unit: all five K tiles requested with Q before the first barrier (K2,K3 were behind a vmcnt(0) after it, K4 in the middle of the QK MFMAs), on top of v4
# speedup vs baseline: 1.0071x; 1.0056x over previous
.LBB0_438:
	v_readlane_b32 s20, v252, 11
	s_add_i32 s20, s36, s20
	s_ashr_i32 s21, s20, 31
	s_lshl_b64 s[20:21], s[20:21], 2
	s_waitcnt lgkmcnt(0)
	s_add_u32 s20, s34, s20
	s_addc_u32 s21, s35, s21
	global_load_dword v137, v209, s[20:21]
	v_mov_b32_e32 v195, 0
	s_mov_b64 s[20:21], exec
	v_readlane_b32 s36, v253, 33
	v_readlane_b32 s37, v253, 34
	s_and_b64 s[36:37], s[20:21], s[36:37]
	s_mov_b64 exec, s[36:37]
	s_cbranch_execz .LBB0_440
	v_add_u32_e32 v36, s53, v142
	v_readlane_b32 s36, v253, 35
	v_ashrrev_i32_e32 v37, 31, v36
	v_readlane_b32 s37, v253, 36
	s_nop 1
	v_lshl_add_u64 v[36:37], v[36:37], 2, s[36:37]
	global_load_dword v195, v[36:37], off
.LBB0_440:
	s_or_b64 exec, exec, s[20:21]
	v_add_u32_e32 v38, s52, v144
	v_mov_b64_e32 v[36:37], s[30:31]
	v_mad_i64_i32 v[36:37], s[20:21], v38, s42, v[36:37]
	v_readlane_b32 s20, v253, 37
	s_mov_b32 s23, s55
	v_readlane_b32 s21, v253, 38
	v_lshl_add_u64 v[36:37], v[36:37], 0, s[22:23]
	s_or_b64 s[36:37], s[44:45], s[20:21]
	v_lshl_add_u64 v[36:37], v[36:37], 0, v[208:209]
	v_cndmask_b32_e64 v38, 0, 1, s[36:37]
	s_andn2_b64 vcc, exec, s[36:37]
	s_mov_b64 s[36:37], 0x1600
	v_cmp_ne_u32_e64 s[20:21], 1, v38
	v_lshl_add_u64 v[40:41], v[36:37], 0, s[36:37]
	s_cbranch_vccnz .LBB0_447
	global_load_dwordx4 v[36:39], v[40:41], off
	s_and_b64 vcc, exec, s[20:21]
	s_cbranch_vccz .LBB0_448

.Lattn_kend:
	s_mov_b32 s23, s55
	v_lshl_add_u64 v[206:207], v[140:141], 0, s[22:23]
	v_lshl_add_u64 v[206:207], v[206:207], 0, v[208:209]
	s_mov_b64 s[20:21], 0x1600
	v_lshl_add_u64 v[206:207], v[206:207], 0, s[20:21]
	global_load_dwordx4 v[198:201], v[206:207], off
	global_load_dwordx4 v[202:205], v[206:207], off offset:32
	global_load_dwordx4 v[240:243], v[206:207], off offset:64
	global_load_dwordx4 v[216:219], v[206:207], off offset:96
	s_barrier
	s_mov_b64 s[20:21], exec
	v_readlane_b32 s36, v253, 31
	v_readlane_b32 s37, v253, 32
	s_and_b64 s[36:37], s[20:21], s[36:37]
	s_mov_b64 exec, s[36:37]
	s_cbranch_execz .LBB0_442
	s_waitcnt vmcnt(0)
	ds_write_b32 v143, v195 offset:33792

.LBB0_460:
	v_mfma_f32_32x32x16_bf16 v[48:63], v[20:23], v[0:3], 0
	s_mov_b32 s23, s55
	s_movk_i32 s20, 0x1000
	v_mfma_f32_32x32x16_bf16 v[48:63], v[24:27], v[90:93], v[48:63]
	v_mfma_f32_32x32x16_bf16 v[48:63], v[28:31], v[86:89], v[48:63]
	v_mfma_f32_32x32x16_bf16 v[64:79], v[4:7], v[0:3], 0
	v_lshl_add_u64 v[4:5], v[140:141], 0, s[22:23]
	v_mfma_f32_32x32x16_bf16 v[48:63], v[32:35], v[82:85], v[48:63]
	s_waitcnt vmcnt(0)
	v_mfma_f32_32x32x16_bf16 v[32:47], v[36:39], v[0:3], 0
	v_mfma_f32_32x32x16_bf16 v[64:79], v[8:11], v[90:93], v[64:79]
	v_lshl_add_u64 v[8:9], v[4:5], 0, v[208:209]
	v_add_co_u32_e32 v4, vcc, s20, v8
	s_mov_b64 s[20:21], 0x1600
	s_nop 0
	v_addc_co_u32_e32 v5, vcc, 0, v9, vcc
	v_mfma_f32_32x32x16_bf16 v[32:47], v[94:97], v[90:93], v[32:47]
	v_mfma_f32_32x32x16_bf16 v[32:47], v[98:101], v[86:89], v[32:47]
	v_lshl_add_u64 v[98:99], v[8:9], 0, s[20:21]
	v_readlane_b32 s20, v253, 39
	v_readlane_b32 s21, v253, 40
	s_or_b64 s[36:37], s[44:45], s[20:21]
	v_mfma_f32_32x32x16_bf16 v[64:79], v[12:15], v[86:89], v[64:79]
	v_mfma_f32_32x32x16_bf16 v[32:47], v[102:105], v[82:85], v[32:47]
	v_mfma_f32_32x32x16_bf16 v[64:79], v[16:19], v[82:85], v[64:79]
	v_mfma_f32_32x32x16_bf16 v[16:31], v[106:109], v[0:3], 0
	v_lshlrev_b32_e32 v98, 1, v124
	s_waitcnt vmcnt(3)
	v_mfma_f32_32x32x16_bf16 v[0:15], v[198:201], v[0:3], 0
	v_mfma_f32_32x32x16_bf16 v[16:31], v[110:113], v[90:93], v[16:31]
	s_waitcnt vmcnt(2)
	v_mfma_f32_32x32x16_bf16 v[0:15], v[202:205], v[90:93], v[0:15]
	v_mov_b32_e32 v94, 0
	v_mov_b32_e32 v95, 0
	v_mov_b32_e32 v96, 0
	v_mov_b32_e32 v97, 0
	v_mfma_f32_32x32x16_bf16 v[16:31], v[114:117], v[86:89], v[16:31]
	s_waitcnt vmcnt(0)
	v_mfma_f32_32x32x16_bf16 v[0:15], v[240:243], v[86:89], v[0:15]
	v_mov_b32_e32 v86, 0
	v_mfma_f32_32x32x16_bf16 v[16:31], v[118:121], v[82:85], v[16:31]
	v_mfma_f32_32x32x16_bf16 v[0:15], v[216:219], v[82:85], v[0:15]
	s_and_saveexec_b64 s[20:21], s[36:37]
	s_cbranch_execz .LBB0_462
	v_add_u32_e32 v84, s52, v148
	v_mov_b64_e32 v[82:83], s[30:31]
	v_mad_i64_i32 v[82:83], s[36:37], v84, s42, v[82:83]
	v_lshl_add_u64 v[82:83], v[82:83], 0, s[22:23]
	v_mov_b32_e32 v99, v209
	v_lshl_add_u64 v[82:83], v[82:83], 0, v[98:99]
	v_add_co_u32_e32 v82, vcc, 0x1000, v82
	s_nop 1
	v_addc_co_u32_e32 v83, vcc, 0, v83, vcc
	global_load_dwordx4 v[94:97], v[82:83], off offset:1792
